# chunk-MLP items: 8 row-per-lane dwordx2 stores per lane widened to 4 dwordx4 with v_permlane16_swap (store-issue-bound part 2); no alignment pads
# baseline (speedup 1.0000x reference)
.Lcma_hd:
	s_add_u32 s8, s30, 0x800000
	s_addc_u32 s9, s31, 0
	s_mov_b32 s4, 0x3a800000
	v_readlane_b32 s36, v254, 21
	v_readlane_b32 s37, v254, 22
	v_readlane_b32 s38, v254, 19
	v_readlane_b32 s39, v254, 20
	v_readlane_b32 s40, v254, 25
	v_readlane_b32 s41, v254, 26
	v_readlane_b32 s42, v254, 41
	v_readlane_b32 s43, v254, 42
	v_readlane_b32 s44, v254, 43
	v_readlane_b32 s45, v254, 44
	v_readlane_b32 s96, v254, 45
	v_readlane_b32 s97, v254, 46
	v_and_b32_e32 v1, 15, v195
	v_lshrrev_b32_e32 v0, 4, v195
	v_lshlrev_b32_e32 v2, 4, v1
	v_lshl_add_u32 v200, v0, 11, v2
	v_add_u32_e32 v201, 0x10000, v200
	v_add_u32_e32 v202, 0x20000, v200
	v_add_u32_e32 v203, 0x30000, v200
	v_lshl_add_u32 v204, v0, 8, v2
	v_add_u32_e32 v205, 0x2000, v204
	v_add_u32_e32 v206, 0x4000, v204
	v_add_u32_e32 v207, 0x6000, v204
	v_and_b32_e32 v3, 0x7f, v195
	v_lshlrev_b32_e32 v208, 7, v3
	v_lshlrev_b32_e32 v209, 5, v1
	v_lshrrev_b32_e32 v4, 6, v195
	v_lshl_add_u32 v5, v4, 4, v1
	v_lshlrev_b32_e32 v210, 2, v5
	v_bfe_u32 v6, v195, 4, 2
	v_lshlrev_b32_e32 v7, 3, v6
	v_lshl_add_u32 v211, v5, 11, v7
	v_and_b32_e32 v219, 1, v6
	v_mul_u32_u24_e32 v219, 24, v219
	v_add_u32_e32 v218, v211, v219
	v_mul_u32_u24_e32 v8, 0x120, v0
	v_add_u32_e32 v212, v8, v2
	v_mul_u32_u24_e32 v8, 0x110, v0
	v_add_u32_e32 v8, v8, v2
	v_add_u32_e32 v213, 0x9000, v8
	v_lshlrev_b32_e32 v8, 3, v0
	v_add_u32_e32 v214, 0x11800, v8
	v_lshlrev_b32_e32 v8, 3, v195
	v_add_u32_e32 v215, 0x11800, v8
	v_lshrrev_b32_e32 v8, 2, v1
	v_lshl_or_b32 v8, v6, 2, v8
	v_mul_u32_u24_e32 v8, 0x120, v8
	v_and_b32_e32 v9, 3, v195
	v_lshl_add_u32 v216, v9, 3, v8
	v_mul_u32_u24_e32 v8, 0x110, v5
	v_add_u32_e32 v8, v8, v7
	v_add_u32_e32 v217, 0x9000, v8
	s_mov_b32 s0, s5
	s_and_b32 s1, s0, 7
	s_lshr_b32 s0, s0, 3
	s_lshl_b32 s0, s0, 7
	s_lshl_b32 s10, s1, 8
	s_lshl_b32 s11, s0, 11
	s_add_u32 s11, s11, s10
	s_add_u32 s46, s42, s11
	s_addc_u32 s47, s43, 0
	s_add_u32 s6, s96, s11
	s_addc_u32 s7, s97, 0
	s_lshl_b32 s10, s1, 15
	s_add_u32 s48, s8, s10
	s_addc_u32 s49, s9, 0
	s_lshl_b32 s10, s0, 7
	s_add_u32 s50, s44, s10
	s_addc_u32 s51, s45, 0
	s_lshl_b32 s10, s1, 9
	s_add_u32 s14, s36, s10
	s_addc_u32 s15, s37, 0
	s_add_u32 s16, s38, s10
	s_addc_u32 s17, s39, 0
	s_add_u32 s10, s40, s10
	s_addc_u32 s11, s41, 0
	v_readfirstlane_b32 s0, v195
	s_nop 1
	s_cmp_lt_u32 s0, 0x80
	s_cbranch_scc0 .Lcma_pf0
	global_load_dwordx4 v[132:135], v208, s[50:51]
	global_load_dwordx4 v[136:139], v208, s[50:51] offset:16
	global_load_dwordx4 v[140:143], v208, s[50:51] offset:32
	global_load_dwordx4 v[144:147], v208, s[50:51] offset:48
	global_load_dwordx4 v[148:151], v208, s[50:51] offset:64
	global_load_dwordx4 v[152:155], v208, s[50:51] offset:80
	global_load_dwordx4 v[156:159], v208, s[50:51] offset:96
	global_load_dwordx4 v[160:163], v208, s[50:51] offset:112

.Lcma_top:
	s_waitcnt vmcnt(4)

.Lcma_nopf:
	s_waitcnt lgkmcnt(0)
	s_barrier
	ds_read_b64 v[88:89], v214
	ds_read_b64 v[90:91], v214 offset:256
	ds_read_b64 v[92:93], v214 offset:512
	ds_read_b64 v[94:95], v214 offset:768
	s_waitcnt lgkmcnt(3)
	v_lshlrev_b32_e32 v56, 16, v0
	v_and_b32_e32 v57, 0xffff0000, v0
	v_lshlrev_b32_e32 v58, 16, v1
	v_and_b32_e32 v59, 0xffff0000, v1
	v_lshlrev_b32_e32 v60, 16, v2
	v_and_b32_e32 v61, 0xffff0000, v2
	v_lshlrev_b32_e32 v62, 16, v3
	v_and_b32_e32 v63, 0xffff0000, v3
	v_sub_f32_e32 v56, v56, v88
	v_sub_f32_e32 v57, v57, v88
	v_sub_f32_e32 v58, v58, v88
	v_sub_f32_e32 v59, v59, v88
	v_sub_f32_e32 v60, v60, v88
	v_sub_f32_e32 v61, v61, v88
	v_sub_f32_e32 v62, v62, v88
	v_sub_f32_e32 v63, v63, v88
	v_mul_f32_e32 v56, v89, v56
	v_mul_f32_e32 v57, v89, v57
	v_mul_f32_e32 v58, v89, v58
	v_mul_f32_e32 v59, v89, v59
	v_mul_f32_e32 v60, v89, v60
	v_mul_f32_e32 v61, v89, v61
	v_mul_f32_e32 v62, v89, v62
	v_mul_f32_e32 v63, v89, v63
	v_fma_f32 v56, v42, v56, v38
	v_fma_f32 v57, v43, v57, v39
	v_fma_f32 v58, v44, v58, v40
	v_fma_f32 v59, v45, v59, v41
	v_fma_f32 v60, v46, v60, v50
	v_fma_f32 v61, v47, v61, v51
	v_fma_f32 v62, v48, v62, v52
	v_fma_f32 v63, v49, v63, v53
	v_cvt_pk_bf16_f32 v64, v56, v57
	v_cvt_pk_bf16_f32 v65, v58, v59
	v_cvt_pk_bf16_f32 v66, v60, v61
	v_cvt_pk_bf16_f32 v67, v62, v63
	ds_write_b128 v212, v[64:67]
	ds_write_b128 v213, v[16:19]
	s_waitcnt lgkmcnt(4)
	v_lshlrev_b32_e32 v56, 16, v4
	v_and_b32_e32 v57, 0xffff0000, v4
	v_lshlrev_b32_e32 v58, 16, v5
	v_and_b32_e32 v59, 0xffff0000, v5
	v_lshlrev_b32_e32 v60, 16, v6
	v_and_b32_e32 v61, 0xffff0000, v6
	v_lshlrev_b32_e32 v62, 16, v7
	v_and_b32_e32 v63, 0xffff0000, v7
	v_sub_f32_e32 v56, v56, v90
	v_sub_f32_e32 v57, v57, v90
	v_sub_f32_e32 v58, v58, v90
	v_sub_f32_e32 v59, v59, v90
	v_sub_f32_e32 v60, v60, v90
	v_sub_f32_e32 v61, v61, v90
	v_sub_f32_e32 v62, v62, v90
	v_sub_f32_e32 v63, v63, v90
	v_mul_f32_e32 v56, v91, v56
	v_mul_f32_e32 v57, v91, v57
	v_mul_f32_e32 v58, v91, v58
	v_mul_f32_e32 v59, v91, v59
	v_mul_f32_e32 v60, v91, v60
	v_mul_f32_e32 v61, v91, v61
	v_mul_f32_e32 v62, v91, v62
	v_mul_f32_e32 v63, v91, v63
	v_fma_f32 v56, v42, v56, v38
	v_fma_f32 v57, v43, v57, v39
	v_fma_f32 v58, v44, v58, v40
	v_fma_f32 v59, v45, v59, v41
	v_fma_f32 v60, v46, v60, v50
	v_fma_f32 v61, v47, v61, v51
	v_fma_f32 v62, v48, v62, v52
	v_fma_f32 v63, v49, v63, v53
	v_cvt_pk_bf16_f32 v64, v56, v57
	v_cvt_pk_bf16_f32 v65, v58, v59
	v_cvt_pk_bf16_f32 v66, v60, v61
	v_cvt_pk_bf16_f32 v67, v62, v63
	ds_write_b128 v212, v[64:67] offset:9216
	ds_write_b128 v213, v[20:23] offset:8704
	s_waitcnt lgkmcnt(5)
	v_lshlrev_b32_e32 v56, 16, v8
	v_and_b32_e32 v57, 0xffff0000, v8
	v_lshlrev_b32_e32 v58, 16, v9
	v_and_b32_e32 v59, 0xffff0000, v9
	v_lshlrev_b32_e32 v60, 16, v10
	v_and_b32_e32 v61, 0xffff0000, v10
	v_lshlrev_b32_e32 v62, 16, v11
	v_and_b32_e32 v63, 0xffff0000, v11
	v_sub_f32_e32 v56, v56, v92
	v_sub_f32_e32 v57, v57, v92
	v_sub_f32_e32 v58, v58, v92
	v_sub_f32_e32 v59, v59, v92
	v_sub_f32_e32 v60, v60, v92
	v_sub_f32_e32 v61, v61, v92
	v_sub_f32_e32 v62, v62, v92
	v_sub_f32_e32 v63, v63, v92
	v_mul_f32_e32 v56, v93, v56
	v_mul_f32_e32 v57, v93, v57
	v_mul_f32_e32 v58, v93, v58
	v_mul_f32_e32 v59, v93, v59
	v_mul_f32_e32 v60, v93, v60
	v_mul_f32_e32 v61, v93, v61
	v_mul_f32_e32 v62, v93, v62
	v_mul_f32_e32 v63, v93, v63
	v_fma_f32 v56, v42, v56, v38
	v_fma_f32 v57, v43, v57, v39
	v_fma_f32 v58, v44, v58, v40
	v_fma_f32 v59, v45, v59, v41
	v_fma_f32 v60, v46, v60, v50
	v_fma_f32 v61, v47, v61, v51
	v_fma_f32 v62, v48, v62, v52
	v_fma_f32 v63, v49, v63, v53
	v_cvt_pk_bf16_f32 v64, v56, v57
	v_cvt_pk_bf16_f32 v65, v58, v59
	v_cvt_pk_bf16_f32 v66, v60, v61
	v_cvt_pk_bf16_f32 v67, v62, v63
	ds_write_b128 v212, v[64:67] offset:18432
	ds_write_b128 v213, v[24:27] offset:17408
	s_waitcnt lgkmcnt(6)
	v_lshlrev_b32_e32 v56, 16, v12
	v_and_b32_e32 v57, 0xffff0000, v12
	v_lshlrev_b32_e32 v58, 16, v13
	v_and_b32_e32 v59, 0xffff0000, v13
	v_lshlrev_b32_e32 v60, 16, v14
	v_and_b32_e32 v61, 0xffff0000, v14
	v_lshlrev_b32_e32 v62, 16, v15
	v_and_b32_e32 v63, 0xffff0000, v15
	v_sub_f32_e32 v56, v56, v94
	v_sub_f32_e32 v57, v57, v94
	v_sub_f32_e32 v58, v58, v94
	v_sub_f32_e32 v59, v59, v94
	v_sub_f32_e32 v60, v60, v94
	v_sub_f32_e32 v61, v61, v94
	v_sub_f32_e32 v62, v62, v94
	v_sub_f32_e32 v63, v63, v94
	v_mul_f32_e32 v56, v95, v56
	v_mul_f32_e32 v57, v95, v57
	v_mul_f32_e32 v58, v95, v58
	v_mul_f32_e32 v59, v95, v59
	v_mul_f32_e32 v60, v95, v60
	v_mul_f32_e32 v61, v95, v61
	v_mul_f32_e32 v62, v95, v62
	v_mul_f32_e32 v63, v95, v63
	v_fma_f32 v56, v42, v56, v38
	v_fma_f32 v57, v43, v57, v39
	v_fma_f32 v58, v44, v58, v40
	v_fma_f32 v59, v45, v59, v41
	v_fma_f32 v60, v46, v60, v50
	v_fma_f32 v61, v47, v61, v51
	v_fma_f32 v62, v48, v62, v52
	v_fma_f32 v63, v49, v63, v53
	v_cvt_pk_bf16_f32 v64, v56, v57
	v_cvt_pk_bf16_f32 v65, v58, v59
	v_cvt_pk_bf16_f32 v66, v60, v61
	v_cvt_pk_bf16_f32 v67, v62, v63
	ds_write_b128 v212, v[64:67] offset:27648
	ds_write_b128 v213, v[28:31] offset:26112
	s_waitcnt lgkmcnt(0)
	s_barrier
	ds_read2_b64 v[12:15], v217 offset1:4
	ds_read2_b64 v[8:11], v217 offset0:8 offset1:12
	ds_read2_b64 v[0:3], v217 offset0:16 offset1:20
	ds_read2_b64 v[4:7], v217 offset0:24 offset1:28
	ds_read_b64_tr_b16 v[18:19], v216
	ds_read_b64_tr_b16 v[20:21], v216 offset:4608
	ds_read_b64_tr_b16 v[22:23], v216 offset:9216
	ds_read_b64_tr_b16 v[24:25], v216 offset:13824
	ds_read_b64_tr_b16 v[26:27], v216 offset:18432
	ds_read_b64_tr_b16 v[28:29], v216 offset:23040
	ds_read_b64_tr_b16 v[30:31], v216 offset:27648
	ds_read_b64_tr_b16 v[32:33], v216 offset:32256
	s_waitcnt lgkmcnt(0)
	ds_read_b64_tr_b16 v[54:55], v216 offset:32
	ds_read_b64_tr_b16 v[56:57], v216 offset:4640
	ds_read_b64_tr_b16 v[58:59], v216 offset:9248
	ds_read_b64_tr_b16 v[60:61], v216 offset:13856
	ds_read_b64_tr_b16 v[62:63], v216 offset:18464
	ds_read_b64_tr_b16 v[64:65], v216 offset:23072
	ds_read_b64_tr_b16 v[66:67], v216 offset:27680
	ds_read_b64_tr_b16 v[68:69], v216 offset:32288
	v_mfma_f32_16x16x32_bf16 v[34:37], v[18:21], v[12:15], 0
	v_mfma_f32_16x16x32_bf16 v[34:37], v[22:25], v[8:11], v[34:37]
	v_mfma_f32_16x16x32_bf16 v[34:37], v[26:29], v[0:3], v[34:37]
	v_mfma_f32_16x16x32_bf16 v[34:37], v[30:33], v[4:7], v[34:37]
	s_waitcnt lgkmcnt(0)
	ds_read_b64_tr_b16 v[18:19], v216 offset:64
	ds_read_b64_tr_b16 v[20:21], v216 offset:4672
	ds_read_b64_tr_b16 v[22:23], v216 offset:9280
	ds_read_b64_tr_b16 v[24:25], v216 offset:13888
	ds_read_b64_tr_b16 v[26:27], v216 offset:18496
	ds_read_b64_tr_b16 v[28:29], v216 offset:23104
	ds_read_b64_tr_b16 v[30:31], v216 offset:27712
	ds_read_b64_tr_b16 v[32:33], v216 offset:32320
	v_mfma_f32_16x16x32_bf16 v[88:91], v[54:57], v[12:15], 0
	v_lshlrev_b32_e32 v38, 16, v70
	v_and_b32_e32 v39, 0xffff0000, v70
	v_lshlrev_b32_e32 v40, 16, v71
	v_and_b32_e32 v41, 0xffff0000, v71
	v_mfma_f32_16x16x32_bf16 v[88:91], v[58:61], v[8:11], v[88:91]
	v_add_f32_e32 v42, v86, v34
	v_add_f32_e32 v43, v86, v35
	v_add_f32_e32 v44, v86, v36
	v_add_f32_e32 v45, v86, v37
	v_mfma_f32_16x16x32_bf16 v[88:91], v[62:65], v[0:3], v[88:91]
	v_mul_f32_e32 v42, v42, v38
	v_mul_f32_e32 v43, v43, v39
	v_mul_f32_e32 v44, v44, v40
	v_mul_f32_e32 v45, v45, v41
	v_mfma_f32_16x16x32_bf16 v[88:91], v[66:69], v[4:7], v[88:91]
	v_cvt_pk_bf16_f32 v48, v42, v43
	v_cvt_pk_bf16_f32 v49, v44, v45
	s_waitcnt lgkmcnt(0)
	ds_read_b64_tr_b16 v[54:55], v216 offset:96
	ds_read_b64_tr_b16 v[56:57], v216 offset:4704
	ds_read_b64_tr_b16 v[58:59], v216 offset:9312
	ds_read_b64_tr_b16 v[60:61], v216 offset:13920
	ds_read_b64_tr_b16 v[62:63], v216 offset:18528
	ds_read_b64_tr_b16 v[64:65], v216 offset:23136
	ds_read_b64_tr_b16 v[66:67], v216 offset:27744
	ds_read_b64_tr_b16 v[68:69], v216 offset:32352
	v_mfma_f32_16x16x32_bf16 v[34:37], v[18:21], v[12:15], 0
	v_lshlrev_b32_e32 v38, 16, v72
	v_and_b32_e32 v39, 0xffff0000, v72
	v_lshlrev_b32_e32 v40, 16, v73
	v_and_b32_e32 v41, 0xffff0000, v73
	v_mfma_f32_16x16x32_bf16 v[34:37], v[22:25], v[8:11], v[34:37]
	v_add_f32_e32 v42, v86, v88
	v_add_f32_e32 v43, v86, v89
	v_add_f32_e32 v44, v86, v90
	v_add_f32_e32 v45, v86, v91
	v_mfma_f32_16x16x32_bf16 v[34:37], v[26:29], v[0:3], v[34:37]
	v_mul_f32_e32 v42, v42, v38
	v_mul_f32_e32 v43, v43, v39
	v_mul_f32_e32 v44, v44, v40
	v_mul_f32_e32 v45, v45, v41
	v_mfma_f32_16x16x32_bf16 v[34:37], v[30:33], v[4:7], v[34:37]
	v_cvt_pk_bf16_f32 v50, v42, v43
	v_cvt_pk_bf16_f32 v51, v44, v45
	s_nop 1
	v_permlane16_swap_b32 v48, v50
	v_permlane16_swap_b32 v49, v51
	global_store_dwordx4 v218, v[48:51], s[12:13]
	s_waitcnt lgkmcnt(0)
	ds_read_b64_tr_b16 v[18:19], v216 offset:128
	ds_read_b64_tr_b16 v[20:21], v216 offset:4736
	ds_read_b64_tr_b16 v[22:23], v216 offset:9344
	ds_read_b64_tr_b16 v[24:25], v216 offset:13952
	ds_read_b64_tr_b16 v[26:27], v216 offset:18560
	ds_read_b64_tr_b16 v[28:29], v216 offset:23168
	ds_read_b64_tr_b16 v[30:31], v216 offset:27776
	ds_read_b64_tr_b16 v[32:33], v216 offset:32384
	v_mfma_f32_16x16x32_bf16 v[88:91], v[54:57], v[12:15], 0
	v_lshlrev_b32_e32 v38, 16, v74
	v_and_b32_e32 v39, 0xffff0000, v74
	v_lshlrev_b32_e32 v40, 16, v75
	v_and_b32_e32 v41, 0xffff0000, v75
	v_mfma_f32_16x16x32_bf16 v[88:91], v[58:61], v[8:11], v[88:91]
	v_add_f32_e32 v42, v86, v34
	v_add_f32_e32 v43, v86, v35
	v_add_f32_e32 v44, v86, v36
	v_add_f32_e32 v45, v86, v37
	v_mfma_f32_16x16x32_bf16 v[88:91], v[62:65], v[0:3], v[88:91]
	v_mul_f32_e32 v42, v42, v38
	v_mul_f32_e32 v43, v43, v39
	v_mul_f32_e32 v44, v44, v40
	v_mul_f32_e32 v45, v45, v41
	v_mfma_f32_16x16x32_bf16 v[88:91], v[66:69], v[4:7], v[88:91]
	v_cvt_pk_bf16_f32 v48, v42, v43
	v_cvt_pk_bf16_f32 v49, v44, v45
	s_waitcnt lgkmcnt(0)
	ds_read_b64_tr_b16 v[54:55], v216 offset:160
	ds_read_b64_tr_b16 v[56:57], v216 offset:4768
	ds_read_b64_tr_b16 v[58:59], v216 offset:9376
	ds_read_b64_tr_b16 v[60:61], v216 offset:13984
	ds_read_b64_tr_b16 v[62:63], v216 offset:18592
	ds_read_b64_tr_b16 v[64:65], v216 offset:23200
	ds_read_b64_tr_b16 v[66:67], v216 offset:27808
	ds_read_b64_tr_b16 v[68:69], v216 offset:32416
	v_mfma_f32_16x16x32_bf16 v[34:37], v[18:21], v[12:15], 0
	v_lshlrev_b32_e32 v38, 16, v76
	v_and_b32_e32 v39, 0xffff0000, v76
	v_lshlrev_b32_e32 v40, 16, v77
	v_and_b32_e32 v41, 0xffff0000, v77
	v_mfma_f32_16x16x32_bf16 v[34:37], v[22:25], v[8:11], v[34:37]
	v_add_f32_e32 v42, v86, v88
	v_add_f32_e32 v43, v86, v89
	v_add_f32_e32 v44, v86, v90
	v_add_f32_e32 v45, v86, v91
	v_mfma_f32_16x16x32_bf16 v[34:37], v[26:29], v[0:3], v[34:37]
	v_mul_f32_e32 v42, v42, v38
	v_mul_f32_e32 v43, v43, v39
	v_mul_f32_e32 v44, v44, v40
	v_mul_f32_e32 v45, v45, v41
	v_mfma_f32_16x16x32_bf16 v[34:37], v[30:33], v[4:7], v[34:37]
	v_cvt_pk_bf16_f32 v50, v42, v43
	v_cvt_pk_bf16_f32 v51, v44, v45
	s_nop 1
	v_permlane16_swap_b32 v48, v50
	v_permlane16_swap_b32 v49, v51
	global_store_dwordx4 v218, v[48:51], s[12:13] offset:64
	s_waitcnt lgkmcnt(0)
	ds_read_b64_tr_b16 v[18:19], v216 offset:192
	ds_read_b64_tr_b16 v[20:21], v216 offset:4800
	ds_read_b64_tr_b16 v[22:23], v216 offset:9408
	ds_read_b64_tr_b16 v[24:25], v216 offset:14016
	ds_read_b64_tr_b16 v[26:27], v216 offset:18624
	ds_read_b64_tr_b16 v[28:29], v216 offset:23232
	ds_read_b64_tr_b16 v[30:31], v216 offset:27840
	ds_read_b64_tr_b16 v[32:33], v216 offset:32448
	v_mfma_f32_16x16x32_bf16 v[88:91], v[54:57], v[12:15], 0
	v_lshlrev_b32_e32 v38, 16, v78
	v_and_b32_e32 v39, 0xffff0000, v78
	v_lshlrev_b32_e32 v40, 16, v79
	v_and_b32_e32 v41, 0xffff0000, v79
	v_mfma_f32_16x16x32_bf16 v[88:91], v[58:61], v[8:11], v[88:91]
	v_add_f32_e32 v42, v86, v34
	v_add_f32_e32 v43, v86, v35
	v_add_f32_e32 v44, v86, v36
	v_add_f32_e32 v45, v86, v37
	v_mfma_f32_16x16x32_bf16 v[88:91], v[62:65], v[0:3], v[88:91]
	v_mul_f32_e32 v42, v42, v38
	v_mul_f32_e32 v43, v43, v39
	v_mul_f32_e32 v44, v44, v40
	v_mul_f32_e32 v45, v45, v41
	v_mfma_f32_16x16x32_bf16 v[88:91], v[66:69], v[4:7], v[88:91]
	v_cvt_pk_bf16_f32 v48, v42, v43
	v_cvt_pk_bf16_f32 v49, v44, v45
	s_waitcnt lgkmcnt(0)
	ds_read_b64_tr_b16 v[54:55], v216 offset:224
	ds_read_b64_tr_b16 v[56:57], v216 offset:4832
	ds_read_b64_tr_b16 v[58:59], v216 offset:9440
	ds_read_b64_tr_b16 v[60:61], v216 offset:14048
	ds_read_b64_tr_b16 v[62:63], v216 offset:18656
	ds_read_b64_tr_b16 v[64:65], v216 offset:23264
	ds_read_b64_tr_b16 v[66:67], v216 offset:27872
	ds_read_b64_tr_b16 v[68:69], v216 offset:32480
	v_mfma_f32_16x16x32_bf16 v[34:37], v[18:21], v[12:15], 0
	v_lshlrev_b32_e32 v38, 16, v80
	v_and_b32_e32 v39, 0xffff0000, v80
	v_lshlrev_b32_e32 v40, 16, v81
	v_and_b32_e32 v41, 0xffff0000, v81
	v_mfma_f32_16x16x32_bf16 v[34:37], v[22:25], v[8:11], v[34:37]
	v_add_f32_e32 v42, v86, v88
	v_add_f32_e32 v43, v86, v89
	v_add_f32_e32 v44, v86, v90
	v_add_f32_e32 v45, v86, v91
	v_mfma_f32_16x16x32_bf16 v[34:37], v[26:29], v[0:3], v[34:37]
	v_mul_f32_e32 v42, v42, v38
	v_mul_f32_e32 v43, v43, v39
	v_mul_f32_e32 v44, v44, v40
	v_mul_f32_e32 v45, v45, v41
	v_mfma_f32_16x16x32_bf16 v[34:37], v[30:33], v[4:7], v[34:37]
	v_cvt_pk_bf16_f32 v50, v42, v43
	v_cvt_pk_bf16_f32 v51, v44, v45
	s_nop 1
	v_permlane16_swap_b32 v48, v50
	v_permlane16_swap_b32 v49, v51
	global_store_dwordx4 v218, v[48:51], s[12:13] offset:128
	s_waitcnt lgkmcnt(0)
	v_mfma_f32_16x16x32_bf16 v[88:91], v[54:57], v[12:15], 0
	v_lshlrev_b32_e32 v38, 16, v82
	v_and_b32_e32 v39, 0xffff0000, v82
	v_lshlrev_b32_e32 v40, 16, v83
	v_and_b32_e32 v41, 0xffff0000, v83
	v_mfma_f32_16x16x32_bf16 v[88:91], v[58:61], v[8:11], v[88:91]
	v_add_f32_e32 v42, v86, v34
	v_add_f32_e32 v43, v86, v35
	v_add_f32_e32 v44, v86, v36
	v_add_f32_e32 v45, v86, v37
	v_mfma_f32_16x16x32_bf16 v[88:91], v[62:65], v[0:3], v[88:91]
	v_mul_f32_e32 v42, v42, v38
	v_mul_f32_e32 v43, v43, v39
	v_mul_f32_e32 v44, v44, v40
	v_mul_f32_e32 v45, v45, v41
	v_mfma_f32_16x16x32_bf16 v[88:91], v[66:69], v[4:7], v[88:91]
	v_cvt_pk_bf16_f32 v48, v42, v43
	v_cvt_pk_bf16_f32 v49, v44, v45
	v_lshlrev_b32_e32 v38, 16, v84
	v_and_b32_e32 v39, 0xffff0000, v84
	v_lshlrev_b32_e32 v40, 16, v85
	v_and_b32_e32 v41, 0xffff0000, v85
	s_nop 3
	v_add_f32_e32 v42, v86, v88
	v_add_f32_e32 v43, v86, v89
	v_add_f32_e32 v44, v86, v90
	v_add_f32_e32 v45, v86, v91
	v_mul_f32_e32 v42, v42, v38
	v_mul_f32_e32 v43, v43, v39
	v_mul_f32_e32 v44, v44, v40
	v_mul_f32_e32 v45, v45, v41
	v_cvt_pk_bf16_f32 v50, v42, v43
	v_cvt_pk_bf16_f32 v51, v44, v45
	s_nop 1
	v_permlane16_swap_b32 v48, v50
	v_permlane16_swap_b32 v49, v51
	global_store_dwordx4 v218, v[48:51], s[12:13] offset:192
	s_add_i32 s5, s5, 1
	s_add_i32 s3, s3, -1
	s_cmp_gt_u32 s3, 0
	s_cbranch_scc1 .Lcma_top

.LBB0_890:
	v_readlane_b32 s4, v254, 39
	s_cmpk_lt_u32 s2, 0x80
	v_readlane_b32 s5, v254, 40
	s_cselect_b64 s[0:1], -1, 0
	s_xor_b64 s[4:5], s[4:5], -1
	s_or_b64 s[0:1], s[0:1], s[4:5]
	s_movk_i32 s3, 0x80
	s_and_b64 vcc, exec, s[0:1]
	s_cbranch_vccnz .LBB0_895
	s_cmpk_lt_i32 s2, 0x80
	s_cbranch_scc1 .LBB0_895
	s_mul_i32 s5, s2, 4
	s_add_i32 s5, s5, 256
	s_mov_b32 s3, 4
	s_add_u32 s8, s30, 0x800000
	s_addc_u32 s9, s31, 0
	s_mov_b32 s4, 0x3a800000
	v_readlane_b32 s36, v254, 21
	v_readlane_b32 s37, v254, 22
	v_readlane_b32 s38, v254, 19
	v_readlane_b32 s39, v254, 20
	v_readlane_b32 s40, v254, 25
	v_readlane_b32 s41, v254, 26
	v_readlane_b32 s42, v254, 41
	v_readlane_b32 s43, v254, 42
	v_readlane_b32 s44, v254, 43
	v_readlane_b32 s45, v254, 44
	v_readlane_b32 s96, v254, 45
	v_readlane_b32 s97, v254, 46
	v_and_b32_e32 v1, 15, v195
	v_lshrrev_b32_e32 v0, 4, v195
	v_lshlrev_b32_e32 v2, 4, v1
	v_lshl_add_u32 v200, v0, 11, v2
	v_add_u32_e32 v201, 0x10000, v200
	v_add_u32_e32 v202, 0x20000, v200
	v_add_u32_e32 v203, 0x30000, v200
	v_lshl_add_u32 v204, v0, 8, v2
	v_add_u32_e32 v205, 0x2000, v204
	v_add_u32_e32 v206, 0x4000, v204
	v_add_u32_e32 v207, 0x6000, v204
	v_and_b32_e32 v3, 0x7f, v195
	v_lshlrev_b32_e32 v208, 7, v3
	v_lshlrev_b32_e32 v209, 5, v1
	v_lshrrev_b32_e32 v4, 6, v195
	v_lshl_add_u32 v5, v4, 4, v1
	v_lshlrev_b32_e32 v210, 2, v5
	v_bfe_u32 v6, v195, 4, 2
	v_lshlrev_b32_e32 v7, 3, v6
	v_lshl_add_u32 v211, v5, 11, v7
	v_and_b32_e32 v219, 1, v6
	v_mul_u32_u24_e32 v219, 24, v219
	v_add_u32_e32 v218, v211, v219
	v_mul_u32_u24_e32 v8, 0x120, v0
	v_add_u32_e32 v212, v8, v2
	v_mul_u32_u24_e32 v8, 0x110, v0
	v_add_u32_e32 v8, v8, v2
	v_add_u32_e32 v213, 0x9000, v8
	v_lshlrev_b32_e32 v8, 3, v0
	v_add_u32_e32 v214, 0x11800, v8
	v_lshlrev_b32_e32 v8, 3, v195
	v_add_u32_e32 v215, 0x11800, v8
	v_lshrrev_b32_e32 v8, 2, v1
	v_lshl_or_b32 v8, v6, 2, v8
	v_mul_u32_u24_e32 v8, 0x120, v8
	v_and_b32_e32 v9, 3, v195
	v_lshl_add_u32 v216, v9, 3, v8
	v_mul_u32_u24_e32 v8, 0x110, v5
	v_add_u32_e32 v8, v8, v7
	v_add_u32_e32 v217, 0x9000, v8
	s_mov_b32 s0, s5
	s_and_b32 s1, s0, 7
	s_lshr_b32 s0, s0, 3
	s_lshl_b32 s0, s0, 7
	s_lshl_b32 s10, s1, 8
	s_lshl_b32 s11, s0, 11
	s_add_u32 s11, s11, s10
	s_add_u32 s46, s42, s11
	s_addc_u32 s47, s43, 0
	s_add_u32 s6, s96, s11
	s_addc_u32 s7, s97, 0
	s_lshl_b32 s10, s1, 15
	s_add_u32 s48, s8, s10
	s_addc_u32 s49, s9, 0
	s_lshl_b32 s10, s0, 7
	s_add_u32 s50, s44, s10
	s_addc_u32 s51, s45, 0
	s_lshl_b32 s10, s1, 9
	s_add_u32 s14, s36, s10
	s_addc_u32 s15, s37, 0
	s_add_u32 s16, s38, s10
	s_addc_u32 s17, s39, 0
	s_add_u32 s10, s40, s10
	s_addc_u32 s11, s41, 0
	v_readfirstlane_b32 s0, v195
	s_nop 1
	s_cmp_lt_u32 s0, 0x80
	s_cbranch_scc0 .Lcmb_pf0
	global_load_dwordx4 v[132:135], v208, s[50:51]
	global_load_dwordx4 v[136:139], v208, s[50:51] offset:16
	global_load_dwordx4 v[140:143], v208, s[50:51] offset:32
	global_load_dwordx4 v[144:147], v208, s[50:51] offset:48
	global_load_dwordx4 v[148:151], v208, s[50:51] offset:64
	global_load_dwordx4 v[152:155], v208, s[50:51] offset:80
	global_load_dwordx4 v[156:159], v208, s[50:51] offset:96
	global_load_dwordx4 v[160:163], v208, s[50:51] offset:112
